# stack, all six grid barriers hand-written (site 0 incl. per-XCD count), constant epochs, early invalidate, last leader releases all XCDs
# speedup vs baseline: 1.0304x; 1.0030x over previous
.LBB0_35:
	s_waitcnt lgkmcnt(0)
	v_writelane_b32 v255, s56, 9
	s_cmp_gt_i32 s83, 1
	s_cselect_b64 s[0:1], -1, 0
	v_writelane_b32 v255, s57, 10
	v_writelane_b32 v255, s58, 11
	v_writelane_b32 v255, s59, 12
	v_writelane_b32 v255, s60, 13
	v_writelane_b32 v255, s61, 14
	v_writelane_b32 v255, s62, 15
	v_writelane_b32 v255, s63, 16
	v_writelane_b32 v255, s64, 17
	v_writelane_b32 v255, s65, 18
	v_writelane_b32 v255, s66, 19
	v_writelane_b32 v255, s67, 20
	v_writelane_b32 v255, s68, 21
	v_writelane_b32 v255, s69, 22
	s_and_b64 s[4:5], s[4:5], s[0:1]
	v_writelane_b32 v255, s70, 23
	s_andn2_b64 vcc, exec, s[4:5]
	v_writelane_b32 v255, s71, 24
	s_cbranch_vccnz .LBB0_89
	s_waitcnt vmcnt(0)
	s_barrier
	s_and_saveexec_b64 s[4:5], s[94:95]
	s_cbranch_execz .LBB0_88
	s_add_u32 s6, s80, 0x2380000
	s_addc_u32 s7, s81, 0
	s_mov_b64 exec, 0xffff
	v_mbcnt_lo_u32_b32 v2, -1, 0
	v_lshlrev_b32_e32 v2, 8, v2
	v_add_u32_e32 v2, 0x400, v2
	s_mov_b32 s10, 0
.Lxb0_c:
	global_load_dword v3, v2, s[6:7] sc1
	s_waitcnt vmcnt(0)
	v_readlane_b32 s11, v3, 0
	v_readlane_b32 s16, v3, 1
	s_add_u32 s11, s11, s16
	v_readlane_b32 s16, v3, 2
	s_add_u32 s11, s11, s16
	v_readlane_b32 s16, v3, 3
	s_add_u32 s11, s11, s16
	v_readlane_b32 s16, v3, 4
	s_add_u32 s11, s11, s16
	v_readlane_b32 s16, v3, 5
	s_add_u32 s11, s11, s16
	v_readlane_b32 s16, v3, 6
	s_add_u32 s11, s11, s16
	v_readlane_b32 s16, v3, 7
	s_add_u32 s11, s11, s16
	v_readlane_b32 s16, v3, 8
	s_add_u32 s11, s11, s16
	v_readlane_b32 s16, v3, 9
	s_add_u32 s11, s11, s16
	v_readlane_b32 s16, v3, 10
	s_add_u32 s11, s11, s16
	v_readlane_b32 s16, v3, 11
	s_add_u32 s11, s11, s16
	v_readlane_b32 s16, v3, 12
	s_add_u32 s11, s11, s16
	v_readlane_b32 s16, v3, 13
	s_add_u32 s11, s11, s16
	v_readlane_b32 s16, v3, 14
	s_add_u32 s11, s11, s16
	v_readlane_b32 s16, v3, 15
	s_add_u32 s11, s11, s16
	s_cmp_eq_u32 s11, s3
	s_cbranch_scc1 .Lxb0_ok
	s_add_i32 s10, s10, 1
	s_cmp_gt_u32 s10, 0x100000
	s_cbranch_scc1 .Lxb0_ok
	s_sleep 1
	s_branch .Lxb0_c
.Lxb0_ok:
	v_cmp_ne_u32_e32 vcc, 0, v3
	s_nop 3
	v_readlane_b32 s16, v3, s87
	s_bcnt1_i32_b64 s9, vcc
	s_max_u32 s16, s16, 1
	s_max_u32 s9, s9, 1
	s_mov_b64 exec, 1
	v_mov_b32_e32 v1, 0x23ff0
	v_mov_b32_e32 v2, s16
	v_mov_b32_e32 v3, s9
	ds_write_b32 v1, v2
	ds_write_b32 v1, v3 offset:4
	s_waitcnt lgkmcnt(0)
	v_mov_b32_e32 v1, 0x23ff0
	ds_read_b32 v2, v1
	ds_read_b32 v3, v1 offset:4
	s_add_u32 s6, s80, 0x2380000
	s_addc_u32 s7, s81, 0
	s_lshl_b32 s8, s87, 8
	s_add_i32 s9, s8, 0x1400
	s_add_i32 s8, s8, 0x2400
	v_mov_b32_e32 v4, s9
	v_mov_b32_e32 v5, 1
	global_atomic_add v6, v4, v5, s[6:7] sc0
	buffer_inv sc1
	s_waitcnt vmcnt(0) lgkmcnt(0)
	v_readfirstlane_b32 s10, v6
	v_readfirstlane_b32 s11, v2
	v_readfirstlane_b32 s16, v3
	s_add_i32 s10, s10, 1
	s_mul_i32 s11, s11, 1
	s_cmp_lg_u32 s10, s11
	s_cbranch_scc1 .Lxb_nl_0
	buffer_wbl2 sc1
	s_waitcnt vmcnt(0)
	v_mov_b32_e32 v4, 0x3400
	global_atomic_add v6, v4, v5, s[6:7] sc0
	s_waitcnt vmcnt(0)
	v_readfirstlane_b32 s10, v6
	s_add_i32 s10, s10, 1
	s_mul_i32 s16, s16, 1
	s_cmp_lg_u32 s10, s16
	s_cbranch_scc1 .Lxb_nl_0
	v_mov_b32_e32 v4, 0x2400
	global_atomic_add v4, v5, s[6:7]
	global_atomic_add v4, v5, s[6:7] offset:256
	global_atomic_add v4, v5, s[6:7] offset:512
	global_atomic_add v4, v5, s[6:7] offset:768
	global_atomic_add v4, v5, s[6:7] offset:1024
	global_atomic_add v4, v5, s[6:7] offset:1280
	global_atomic_add v4, v5, s[6:7] offset:1536
	global_atomic_add v4, v5, s[6:7] offset:1792
	global_atomic_add v4, v5, s[6:7] offset:2048
	global_atomic_add v4, v5, s[6:7] offset:2304
	global_atomic_add v4, v5, s[6:7] offset:2560
	global_atomic_add v4, v5, s[6:7] offset:2816
	global_atomic_add v4, v5, s[6:7] offset:3072
	global_atomic_add v4, v5, s[6:7] offset:3328
	global_atomic_add v4, v5, s[6:7] offset:3584
	global_atomic_add v4, v5, s[6:7] offset:3840
	s_branch .Lxb_done_0

.Lxb_nl2_0:
	global_load_dword v6, v4, s[6:7] sc1
	s_waitcnt vmcnt(0)
	v_readfirstlane_b32 s11, v6
	s_cmp_ge_u32 s11, 1
	s_cbranch_scc1 .Lxb_done_0
	s_sleep 1
	s_add_i32 s10, s10, 1
	s_cmp_lt_u32 s10, 0x100000
	s_cbranch_scc1 .Lxb_nl2_0
